# attnA: next-pair LDS-DMA issued in QK MFMA gaps with scalar bases, K/V fragment prefetch right after the barrier
# speedup vs baseline: 1.0109x; 1.0109x over previous
; __device__ __forceinline__ void unitA(LAS char* lds, const gbf* PROJ, const gbf* VT, gbf* Y, const int S, const int tok0, const int h, const int qblk,
;                                       const float lam, const float oml, const gfl* subln, const float kn2a, const float kn2b, const int tid_) {
;     const int tid = opaque_v(tid_);
;     const int lane = tid & 63, r32 = lane & 31, hi = lane >> 5, wid = __builtin_amdgcn_readfirstlane(tid >> 6), rg = wid >> 1, map = wid & 1;
;     const int NT = S >> 6, tstart = qblk * 2;
;     const int q0 = qblk * 128 + rg * 32;
;     const float slope2 = LOG2E * __builtin_amdgcn_exp2f(-2.f * (float)(h + 1)), nslope = -slope2, inv_slope2 = 1.f / slope2;
;     const bool skip_en = slope2 * (float)S > SKIP_MARGIN + 8.f;
;     LAS float* wsf = (LAS float*)(lds + WSFA_OFF) + wid * 64;
;     LAS float* lim = (LAS float*)(lds + LIM_OFF);
;     asm volatile("s_waitcnt vmcnt(0)" ::: "memory");
;     const gbf* ksrc[2]; const gbf* vsrc[2];
; #pragma unroll
;     for (int i = 0; i < 2; ++i) { const int j = 2 * wid + i;
;         { const int row = 4 * j + (lane >> 4), c = (lane & 15) ^ (row & 15); ksrc[i] = PROJ + (size_t)(tok0 + row) * NPROJ + C_KA + h * 128 + c * 8; }
; __global__ void __launch_bounds__(512, 2) mega_fwd(Params p) {
;     ...
;                       for (;;) {
;                           if (tid == 0) *qs = __hip_atomic_fetch_add(qh, 1u, __ATOMIC_RELAXED, __HIP_MEMORY_SCOPE_AGENT);
;                           __syncthreads();
;                           const unsigned j = (unsigned)__builtin_amdgcn_readfirstlane((int)*qs);
;                           __syncthreads();
;                           if (j >= 256u) break;
;                           const int r = (int)(j >> 5), i = ((3 - (r >> 1)) & 3) + 4 * (r & 1), c = ((int)(j & 31u) + 4 * i) & 31, top = i >> 2, h = i & 3;
;                           int b, qblk;
;                           if (NQA == 32) { b = 2 * (int)x + top; qblk = c; } else { b = (int)x; qblk = c + 32 * top; }
;                           const u32x4 kq = *(const GAS u32x4*)(kn2 + b * 16 + h * 4);
;                           const float kn2a = __uint_as_float(kq.x) + __uint_as_float(kq.y), kn2b = __uint_as_float(kq.z) + __uint_as_float(kq.w);
;                           att::unitA((LAS char*)lds, uni(PROJ), uni(VT), uni(Y), S, b * S, h, qblk, lam, oml, subln, unif(kn2a), unif(kn2b), tid);
.LBB0_364:
	s_or_b64 exec, exec, s[4:5]
	v_mov_b32_e32 v0, s15
	s_waitcnt lgkmcnt(0)
	s_barrier
	ds_read_b32 v0, v0
	s_mov_b64 s[4:5], -1
	s_waitcnt lgkmcnt(0)
	s_barrier
	v_readfirstlane_b32 s0, v0
	s_cmpk_gt_u32 s0, 0xff
	s_cbranch_scc1 .LBB0_359
	s_lshr_b32 s4, s0, 3
	s_lshr_b32 s2, s0, 6
	s_and_b32 s4, s4, 4
	s_sub_i32 s2, s4, s2
	s_add_i32 s2, s2, 3
	s_lshl_b32 s4, s2, 2
	s_add_i32 s4, s4, s0
	s_and_b32 s0, s4, 31
	s_lshr_b32 s4, s2, 2
	s_and_b32 s10, s2, 3
	s_add_i32 s2, s4, s1
	s_lshl_b32 s8, s4, 5
	s_and_b64 s[4:5], s[94:95], exec
	s_cselect_b32 s4, 0, s8
	s_or_b32 s24, s0, s4
	s_and_b64 s[4:5], s[94:95], exec
	s_cselect_b32 s0, s2, s90
	s_lshl_b32 s76, s0, 4
	s_lshl_b64 s[4:5], s[76:77], 2
	s_add_u32 s4, s40, s4
	s_addc_u32 s5, s41, s5
	s_lshl_b32 s2, s10, 4
	v_mov_b32_e32 v0, s2
	global_load_dwordx4 v[2:5], v0, s[4:5]
	v_mov_b32_e32 v10, v205
	s_lshl_b32 s11, s0, s87
	s_not_b32 s2, s10
	v_readfirstlane_b32 s0, v10
	s_ashr_i32 s12, s0, 6
	s_ashr_i32 s33, s0, 7
	s_lshl_b32 s88, s33, 5
	s_lshl_b32 s13, s2, 1
	s_and_b32 s2, s0, 0x3fffffc0
	s_lshl_b32 s16, s12, 1
	s_lshl_b32 s0, s10, 7
	s_lshl_b32 s4, s11, 1
	s_add_u32 s4, s34, s4
	v_bfe_u32 v11, v10, 4, 2
	s_addc_u32 s5, s35, 0
	s_lshl_b32 s20, s12, 3
	v_or_b32_e32 v0, s20, v11
	v_bitop3_b32 v13, s20, v10, v11 bitop3:0x36
	v_add_u32_e32 v0, s11, v0
	v_mov_b64_e32 v[6:7], s[92:93]
	s_movk_i32 s17, 0x1e00
	v_mad_i64_i32 v[8:9], s[8:9], v0, s17, v[6:7]
	s_lshl_b32 s76, s10, 8
	v_lshlrev_b32_e32 v0, 4, v13
	v_bfe_u32 v12, v10, 3, 3
	v_lshl_add_u64 v[8:9], v[8:9], 0, s[76:77]
	v_and_b32_e32 v0, 0xf0, v0
	v_lshl_add_u64 v[180:181], v[8:9], 0, v[0:1]
	v_or_b32_e32 v8, s0, v12
	v_lshl_add_u32 v8, s12, 4, v8
	v_xor_b32_e32 v0, v11, v10
	v_ashrrev_i32_e32 v9, 31, v8
	v_lshlrev_b64 v[8:9], 17, v[8:9]
	v_lshlrev_b32_e32 v0, 4, v0
	s_or_b32 s10, s16, 1
	v_lshl_add_u64 v[8:9], s[4:5], 0, v[8:9]
	v_and_b32_e32 v0, 0x70, v0
	s_lshl_b32 s8, s10, 2
	v_lshl_add_u64 v[182:183], v[8:9], 0, v[0:1]
	v_or_b32_e32 v0, s8, v11
	v_bitop3_b32 v11, s8, v10, v11 bitop3:0x36
	v_add_u32_e32 v0, s11, v0
	v_mad_i64_i32 v[8:9], s[8:9], v0, s17, v[6:7]
	v_lshlrev_b32_e32 v0, 4, v11
	v_lshl_add_u64 v[8:9], v[8:9], 0, s[76:77]
	v_and_b32_e32 v0, 0xf0, v0
	v_lshl_add_u64 v[196:197], v[8:9], 0, v[0:1]
	v_lshl_or_b32 v0, s10, 3, v12
	v_lshrrev_b32_e32 v8, 1, v0
	v_xor_b32_e32 v11, v8, v10
	v_add_u32_e32 v8, s0, v0
	v_ashrrev_i32_e32 v9, 31, v8
	v_lshlrev_b64 v[8:9], 17, v[8:9]
	v_lshl_add_u64 v[8:9], s[4:5], 0, v[8:9]
	s_lshl_b32 s5, s24, 7
	v_lshlrev_b32_e32 v0, 4, v11
	s_add_i32 s88, s88, s5
	v_and_b32_e32 v178, 31, v10
	v_and_b32_e32 v0, 0x70, v0
	s_add_i32 s86, s88, s11
	v_lshl_add_u64 v[198:199], v[8:9], 0, v[0:1]
	v_or_b32_e32 v0, s86, v178
	s_and_b32 s4, s12, 1
	v_mad_i64_i32 v[6:7], s[8:9], v0, s17, v[6:7]
	v_bfe_u32 v210, v10, 5, 1
	v_lshl_add_u64 v[6:7], v[6:7], 0, s[76:77]
	s_lshl_b32 s76, s4, 7
	v_lshl_add_u64 v[6:7], v[6:7], 0, s[76:77]
	v_lshlrev_b32_e32 v0, 4, v210
	s_waitcnt vmcnt(0)
	v_lshl_add_u64 v[6:7], v[6:7], 0, v[0:1]
	global_load_dwordx4 v[162:165], v[6:7], off
	global_load_dwordx4 v[166:169], v[6:7], off offset:32
	global_load_dwordx4 v[170:173], v[6:7], off offset:64
	global_load_dwordx4 v[174:177], v[6:7], off offset:96
	s_mov_b32 s8, 0x43100000
	s_waitcnt vmcnt(4)
	v_add_f32_e32 v2, v2, v3
	v_cvt_f32_i32_e32 v3, s13
	v_readfirstlane_b32 s13, v2
	v_add_f32_e32 v4, v4, v5
	s_lshl_b32 s76, s24, 8
	v_exp_f32_e32 v2, v3
	v_readfirstlane_b32 s16, v4
	v_lshlrev_b32_e32 v8, 3, v210
	v_cvt_f32_i32_e32 v239, s88
	v_mul_f32_e32 v211, 0x3fb8aa3b, v2
	v_mul_f32_e32 v2, v211, v209
	v_cmp_lt_f32_e64 s[8:9], s8, v2
	v_div_scale_f32 v2, s[10:11], v211, v211, 1.0
	v_rcp_f32_e32 v3, v2
	s_lshl_b32 s10, s12, 11
	s_add_i32 s91, s10, 0
	s_mov_b32 m0, s91
	v_fma_f32 v4, -v2, v3, 1.0
	v_fmac_f32_e32 v3, v4, v3
	v_div_scale_f32 v4, vcc, 1.0, v211, 1.0
	v_mul_f32_e32 v5, v4, v3
	v_fma_f32 v6, -v2, v5, v4
	v_fmac_f32_e32 v5, v6, v3
	v_fma_f32 v2, -v2, v5, v4
	v_div_fmas_f32 v2, v2, v3, v5
	v_div_fixup_f32 v212, v2, v211, 1.0
	v_mad_u64_u32 v[2:3], s[10:11], s5, v228, v[180:181]
	v_lshl_add_u64 v[2:3], v[2:3], 0, s[80:81]
	global_load_lds_dwordx4 v[2:3], off
	v_mad_u64_u32 v[2:3], s[10:11], s5, v228, v[196:197]
	v_lshl_add_u64 v[2:3], v[2:3], 0, s[80:81]
	s_add_i32 m0, s91, 0x400
	s_or_b32 s5, s5, 64
	global_load_lds_dwordx4 v[2:3], off
	v_lshl_add_u64 v[2:3], v[182:183], 0, s[76:77]
	s_add_i32 m0, s91, 0x4000
	v_lshl_add_u64 v[4:5], v[198:199], 0, s[76:77]
	global_load_lds_dwordx4 v[2:3], off
	s_add_i32 m0, s91, 0x4400
	v_mad_u64_u32 v[6:7], s[10:11], s5, v228, v[180:181]
	global_load_lds_dwordx4 v[4:5], off
	s_add_i32 m0, s91, 0x8000
	v_lshl_add_u64 v[6:7], v[6:7], 0, s[80:81]
	global_load_lds_dwordx4 v[6:7], off
	v_mad_u64_u32 v[6:7], s[10:11], s5, v228, v[196:197]
	v_lshl_add_u64 v[6:7], v[6:7], 0, s[80:81]
	s_add_i32 m0, s91, 0x8400
	v_lshl_add_u64 v[2:3], v[2:3], 0, s[78:79]
	global_load_lds_dwordx4 v[6:7], off
	s_add_i32 m0, s91, 0xc000
	s_mov_b32 s5, 0xf800000
	global_load_lds_dwordx4 v[2:3], off
	v_lshl_add_u64 v[2:3], v[4:5], 0, s[78:79]
	s_add_i32 m0, s91, 0xc400
	s_cmp_eq_u32 s4, 0
	global_load_lds_dwordx4 v[2:3], off
	s_cselect_b64 s[10:11], -1, 0
	s_cmp_eq_u32 s4, 1
	v_and_b32_e32 v179, 63, v10
	v_mov_b32_e32 v16, v1
	v_mov_b32_e32 v17, v1
	v_xor_b32_e32 v200, 0x80000000, v211
	s_waitcnt vmcnt(0)
; __device__ __forceinline__ float bf_lo(unsigned w) { return __uint_as_float(w << 16); }
; __device__ __forceinline__ float bf_hi(unsigned w) { return __uint_as_float(w & 0xffff0000u); }
; __device__ __forceinline__ float sum_x32(float v) { auto rr = __builtin_amdgcn_permlane32_swap(__float_as_uint(v), __float_as_uint(v), false, false); return __uint_as_float(rr[0]) + __uint_as_float(rr[1]); }
; __device__ __forceinline__ int swap23(int r) { return (r & ~12) | ((r & 4) << 1) | ((r & 8) >> 1); }
; __device__ __forceinline__ void unitA(LAS char* lds, const gbf* PROJ, const gbf* VT, gbf* Y, const int S, const int tok0, const int h, const int qblk,
;                                       const float lam, const float oml, const gfl* subln, const float kn2a, const float kn2b, const int tid_) {
;     ...
;         { const int row = 4 * j + (lane >> 4), c = (lane & 15) ^ (row & 15); ksrc[i] = PROJ + (size_t)(tok0 + row) * NPROJ + C_KA + h * 128 + c * 8; }
;         { const int row = 8 * j + (lane >> 3), c = (lane & 7) ^ ((row >> 1) & 7); vsrc[i] = VT + (size_t)(h * 128 + row) * MG + tok0 + c * 8; } }
;     ...
;     { float qn = 0.f;
; #pragma unroll
;       for (int dc = 0; dc < 4; ++dc) { const u32x4 w = __builtin_bit_cast(u32x4, qf[dc]);
;           qn += bf_lo(w.x) * bf_lo(w.x) + bf_hi(w.x) * bf_hi(w.x) + bf_lo(w.y) * bf_lo(w.y) + bf_hi(w.y) * bf_hi(w.y) + bf_lo(w.z) * bf_lo(w.z) + bf_hi(w.z) * bf_hi(w.z) + bf_lo(w.w) * bf_lo(w.w) + bf_hi(w.w) * bf_hi(w.w); }
;       qn = sum_x32(qn);
;       ub = __builtin_sqrtf(qn * ((map ? kn2b : kn2a) * 1.03f)) * 1.002f + 0.05f; }
;     f32x16 o[4];
; #pragma unroll
;     for (int d = 0; d < 4; ++d)
; #pragma unroll
;         for (int r = 0; r < 16; ++r) o[d][r] = 0.f;
;     float mref = 0.f, lsum = 0.f;
;     int kbase[4], vbase[4];
;     { const int krow = swap23(r32), km = krow & 15, vm = (r32 >> 1) & 7;
; #pragma unroll
;       for (int dc = 0; dc < 4; ++dc) kbase[dc] = krow * 256 + (((map * 8 + dc * 2 + hi) ^ km) << 4);
; #pragma unroll
;       for (int c = 0; c < 4; ++c) vbase[c] = A_VOFF + r32 * 128 + (((2 * c + hi) ^ vm) << 4); }
;     const float qposf = (float)(q0 + r32 - 8 * hi);
	v_and_b32_e32 v5, 0xffff0000, v162
	v_lshlrev_b32_e32 v4, 16, v162
	v_mul_f32_e32 v5, v5, v5
	v_fmac_f32_e32 v5, v4, v4
	v_lshlrev_b32_e32 v4, 16, v163
	v_fmac_f32_e32 v5, v4, v4
	v_and_b32_e32 v4, 0xffff0000, v163
	v_fmac_f32_e32 v5, v4, v4
	v_lshlrev_b32_e32 v4, 16, v164
	v_fmac_f32_e32 v5, v4, v4
	v_and_b32_e32 v4, 0xffff0000, v164
	v_fmac_f32_e32 v5, v4, v4
	v_lshlrev_b32_e32 v4, 16, v165
	v_fmac_f32_e32 v5, v4, v4
	v_and_b32_e32 v4, 0xffff0000, v165
	v_and_b32_e32 v6, 0xffff0000, v166
	v_fmac_f32_e32 v5, v4, v4
	v_lshlrev_b32_e32 v4, 16, v166
	v_mul_f32_e32 v6, v6, v6
	v_fmac_f32_e32 v6, v4, v4
	v_lshlrev_b32_e32 v4, 16, v167
	v_fmac_f32_e32 v6, v4, v4
	v_and_b32_e32 v4, 0xffff0000, v167
	v_fmac_f32_e32 v6, v4, v4
	v_lshlrev_b32_e32 v4, 16, v168
	v_fmac_f32_e32 v6, v4, v4
	v_and_b32_e32 v4, 0xffff0000, v168
	v_fmac_f32_e32 v6, v4, v4
	v_lshlrev_b32_e32 v4, 16, v169
	v_fmac_f32_e32 v6, v4, v4
	v_and_b32_e32 v4, 0xffff0000, v169
	v_fmac_f32_e32 v6, v4, v4
	v_add_f32_e32 v4, v5, v6
	v_and_b32_e32 v6, 0xffff0000, v170
	v_lshlrev_b32_e32 v5, 16, v170
	v_mul_f32_e32 v6, v6, v6
	v_fmac_f32_e32 v6, v5, v5
	v_lshlrev_b32_e32 v5, 16, v171
	v_fmac_f32_e32 v6, v5, v5
	v_and_b32_e32 v5, 0xffff0000, v171
	v_fmac_f32_e32 v6, v5, v5
	v_lshlrev_b32_e32 v5, 16, v172
	v_fmac_f32_e32 v6, v5, v5
	v_and_b32_e32 v5, 0xffff0000, v172
	v_fmac_f32_e32 v6, v5, v5
	v_lshlrev_b32_e32 v5, 16, v173
	v_fmac_f32_e32 v6, v5, v5
	v_and_b32_e32 v5, 0xffff0000, v173
	v_fmac_f32_e32 v6, v5, v5
	v_add_f32_e32 v4, v4, v6
	v_and_b32_e32 v6, 0xffff0000, v174
	v_lshlrev_b32_e32 v5, 16, v174
	v_mul_f32_e32 v6, v6, v6
	v_fmac_f32_e32 v6, v5, v5
	v_lshlrev_b32_e32 v5, 16, v175
	v_fmac_f32_e32 v6, v5, v5
	v_and_b32_e32 v5, 0xffff0000, v175
	v_fmac_f32_e32 v6, v5, v5
	v_lshlrev_b32_e32 v5, 16, v176
	v_fmac_f32_e32 v6, v5, v5
	v_and_b32_e32 v5, 0xffff0000, v176
	v_fmac_f32_e32 v6, v5, v5
	v_lshlrev_b32_e32 v5, 16, v177
	v_fmac_f32_e32 v6, v5, v5
	v_and_b32_e32 v5, 0xffff0000, v177
	v_fmac_f32_e32 v6, v5, v5
	v_add_f32_e32 v4, v4, v6
	v_mov_b32_e32 v5, v4
	s_nop 1
	v_permlane32_swap_b32_e32 v4, v5
	v_add_f32_e32 v4, v4, v5
	v_mov_b32_e32 v5, s16
	v_mov_b32_e32 v6, s13
	v_cndmask_b32_e64 v5, v5, v6, s[10:11]
	v_mul_f32_e32 v5, 0x3f83d70a, v5
	v_mul_f32_e32 v4, v5, v4
	v_mul_f32_e32 v5, 0x4f800000, v4
	v_cmp_gt_f32_e32 vcc, s5, v4
	s_cselect_b64 s[16:17], -1, 0
	s_lshl_b32 s2, s2, 2
	v_cndmask_b32_e32 v4, v4, v5, vcc
	v_sqrt_f32_e32 v5, v4
	s_add_i32 s42, s2, 0
	s_lshl_b32 s2, s4, 3
	s_add_i32 s42, s42, 0x20000
	v_add_u32_e32 v2, -1, v5
	v_fma_f32 v3, -v2, v5, v4
	v_cmp_ge_f32_e64 s[12:13], 0, v3
	v_add_u32_e32 v3, 1, v5
	s_add_i32 s30, s20, 0
	v_cndmask_b32_e64 v2, v5, v2, s[12:13]
	v_fma_f32 v5, -v3, v5, v4
	v_cmp_lt_f32_e64 s[12:13], 0, v5
	v_lshrrev_b32_e32 v5, 1, v10
	v_mov_b32_e32 v11, v1
	v_cndmask_b32_e64 v2, v2, v3, s[12:13]
	v_mul_f32_e32 v3, 0x37800000, v2
	v_cndmask_b32_e32 v2, v2, v3, vcc
	v_cmp_class_f32_e32 vcc, v4, v223
	v_and_b32_e32 v3, 19, v10
	v_and_or_b32 v3, v5, 4, v3
	v_cndmask_b32_e32 v2, v2, v4, vcc
	v_lshlrev_b32_e32 v4, 1, v10
	v_and_b32_e32 v4, 8, v4
	v_or_b32_e32 v6, v3, v4
	v_bitop3_b32 v3, v3, 15, v4 bitop3:0xc8
	v_fmamk_f32 v235, v2, 0x3f804189, v224
	v_sub_u32_e32 v2, v178, v8
	v_lshlrev_b32_e32 v4, 8, v6
	v_or_b32_e32 v6, s2, v210
	v_bitop3_b32 v7, s2, v3, v210 bitop3:0x36
	v_add_u32_e32 v2, s88, v2
	v_lshl_or_b32 v213, v7, 4, v4
	v_bitop3_b32 v7, v6, v3, 2 bitop3:0x36
	v_cvt_f32_i32_e32 v236, v2
	v_sub_co_u32_e64 v2, s[82:83], s24, 1
	v_lshl_or_b32 v215, v7, 4, v4
	v_bitop3_b32 v7, v6, v3, 4 bitop3:0x36
	v_bitop3_b32 v3, v6, v3, 6 bitop3:0x36
	v_readfirstlane_b32 s19, v2
	v_lshlrev_b32_e32 v2, 7, v2
	v_lshl_or_b32 v217, v3, 4, v4
	v_bfe_u32 v3, v10, 1, 3
	v_or_b32_e32 v2, 0x7f, v2
	s_or_b32 s2, s88, 31
	v_lshl_or_b32 v216, v7, 4, v4
	v_lshlrev_b32_e32 v4, 7, v178
	v_bitop3_b32 v5, v210, v5, 7 bitop3:0x78
	v_bitop3_b32 v7, v210, v3, 2 bitop3:0x36
	v_bitop3_b32 v9, v210, v3, 4 bitop3:0x36
	v_bitop3_b32 v3, v210, v3, 6 bitop3:0x36
	v_cvt_f32_u32_e32 v237, v2
	v_cvt_f32_i32_e32 v238, s2
	v_or_b32_e32 v6, 0x4000, v4
	v_lshlrev_b32_e32 v5, 4, v5
	v_lshlrev_b32_e32 v7, 4, v7
	v_lshlrev_b32_e32 v9, 4, v9
	v_lshlrev_b32_e32 v3, 4, v3
	v_or_b32_e32 v231, v5, v6
	v_or_b32_e32 v232, v7, v6
	v_or_b32_e32 v233, v9, v6
	v_or_b32_e32 v234, v3, v6
	v_cmp_eq_u32_e32 vcc, 0, v179
	v_or_b32_e32 v240, v5, v4
	v_or_b32_e32 v241, v7, v4
	v_or_b32_e32 v242, v9, v4
	v_or_b32_e32 v243, v3, v4
	v_mov_b32_e32 v2, v1
	v_mov_b32_e32 v3, v1
	v_mov_b32_e32 v4, v1
	v_mov_b32_e32 v5, v1
	v_mov_b32_e32 v6, v1
	v_mov_b32_e32 v7, v1
	v_mov_b32_e32 v8, v1
	v_mov_b32_e32 v9, v1
	v_mov_b32_e32 v10, v1
	v_mov_b32_e32 v12, v1
	v_mov_b32_e32 v13, v1
	v_mov_b32_e32 v14, v1
	v_mov_b32_e32 v15, v1
	v_mov_b64_e32 v[32:33], v[16:17]
	v_mov_b64_e32 v[48:49], v[16:17]
	v_mov_b64_e32 v[64:65], v[16:17]
	s_mov_b32 s44, 0
	s_mov_b32 s45, 1
	v_cmp_gt_u32_e64 s[12:13], 32, v179
	v_lshl_add_u32 v214, v178, 2, s42
	s_and_b64 s[4:5], s[8:9], vcc
	s_add_i32 s30, s30, 0x20800
	v_mov_b32_e32 v202, v200
	v_mov_b32_e32 v203, v200
	s_mov_b32 s38, 0xff61b1e6
	s_mov_b32 s96, 0x7f61b1e6
	v_mov_b32_e32 v204, 0
	v_mov_b32_e32 v244, 0x7f61b1e6
	s_mov_b32 s31, 0
	v_mov_b64_e32 v[30:31], v[14:15]
	v_mov_b64_e32 v[28:29], v[12:13]
	v_mov_b64_e32 v[26:27], v[10:11]
	v_mov_b64_e32 v[24:25], v[8:9]
	v_mov_b64_e32 v[22:23], v[6:7]
	v_mov_b64_e32 v[20:21], v[4:5]
	v_mov_b64_e32 v[18:19], v[2:3]
	v_mov_b64_e32 v[46:47], v[14:15]
	v_mov_b64_e32 v[44:45], v[12:13]
	v_mov_b64_e32 v[42:43], v[10:11]
	v_mov_b64_e32 v[40:41], v[8:9]
	v_mov_b64_e32 v[38:39], v[6:7]
	v_mov_b64_e32 v[36:37], v[4:5]
	v_mov_b64_e32 v[34:35], v[2:3]
	v_mov_b64_e32 v[62:63], v[14:15]
	v_mov_b64_e32 v[60:61], v[12:13]
	v_mov_b64_e32 v[58:59], v[10:11]
	v_mov_b64_e32 v[56:57], v[8:9]
	v_mov_b64_e32 v[54:55], v[6:7]
	v_mov_b64_e32 v[52:53], v[4:5]
	v_mov_b64_e32 v[50:51], v[2:3]
	v_mov_b32_e32 v248, 0
	s_mov_b32 s36, 0
	s_mov_b32 s37, s24
	v_readfirstlane_b32 s48, v180
	v_readfirstlane_b32 s49, v181
	v_readfirstlane_b32 s50, v182
	v_readfirstlane_b32 s51, v183
	s_nop 3
	s_sub_u32 s48, s48, 0x100
	s_subb_u32 s49, s49, 0
	s_sub_u32 s50, s50, 0x100
	s_subb_u32 s51, s51, 0
	s_nop 1
	v_subrev_u32_e32 v180, s48, v180
	v_subrev_u32_e32 v196, s48, v196
	v_subrev_u32_e32 v182, s50, v182
	v_subrev_u32_e32 v198, s50, v198
	s_add_u32 s48, s48, 0x400
	s_addc_u32 s49, s49, 0
; #define LAS __attribute__((address_space(3)))
; __device__ __forceinline__ float unif(float v) { return __int_as_float(__builtin_amdgcn_readfirstlane(__float_as_int(v))); }
; __device__ __forceinline__ void unitA(LAS char* lds, const gbf* PROJ, const gbf* VT, gbf* Y, const int S, const int tok0, const int h, const int qblk,
;                                       const float lam, const float oml, const gfl* subln, const float kn2a, const float kn2b, const int tid_) {
;     ...
;         asm volatile("s_waitcnt vmcnt(0) lgkmcnt(0)\n\ts_barrier" ::: "memory");
;         if (skip_en && it > 0) { const LAS f32x4* lp = (const LAS f32x4*)(lim + ((it - 1) & 1) * 16); const f32x4 a = lp[0], b = lp[1], c = lp[2], d = lp[3];
;             blkR = __builtin_fmaxf(__builtin_fmaxf(__builtin_fmaxf(a[0], a[2]), __builtin_fmaxf(b[0], b[2])), __builtin_fmaxf(__builtin_fmaxf(c[0], c[2]), __builtin_fmaxf(d[0], d[2])));
;             blkL = __builtin_fminf(__builtin_fminf(__builtin_fminf(a[1], a[3]), __builtin_fminf(b[1], b[3])), __builtin_fminf(__builtin_fminf(c[1], c[3]), __builtin_fminf(d[1], d[3])));
;             blkR = unif(blkR); blkL = unif(blkL); }
;     ...
;           const int kv0 = tA * 128 + sub * 64, sb = (2 * (it & 1) + sub) * A_STAGE; const float dbase = (float)kv0 - qposf;
;           int kad[4], vad[4];
; #pragma unroll
;           for (int k = 0; k < 4; ++k) { kad[k] = kbase[k] + sb; vad[k] = vbase[k] + sb; }
.LBB0_366:
	s_cmp_lg_u32 s36, 0
	s_cselect_b64 s[20:21], -1, 0
	s_waitcnt vmcnt(0) lgkmcnt(0)
	s_barrier
	s_and_b32 s89, s44, 0x10000
	v_add_u32_e32 v245, s89, v213
	v_add_u32_e32 v246, s89, v215
	v_add_u32_e32 v247, s89, v216
	v_add_u32_e32 v250, s89, v217
	v_add_u32_e32 v184, s89, v240
	v_add_u32_e32 v185, s89, v241
	v_add_u32_e32 v186, s89, v242
	v_add_u32_e32 v187, s89, v243
	s_and_b64 s[20:21], s[8:9], s[20:21]
	s_andn2_b64 vcc, exec, s[20:21]
	s_cbranch_vccnz .LBB0_369
	s_andn2_b32 s20, 16, s31
	s_lshl_b32 s20, s20, 2
	s_add_i32 s20, s20, 0
	s_add_i32 s20, s20, 0x20800
	v_mov_b32_e32 v78, s20
	ds_read_b128 v[66:69], v78
	ds_read_b128 v[70:73], v78 offset:16
	ds_read_b128 v[74:77], v78 offset:32
	ds_read_b128 v[78:81], v78 offset:48
	ds_read_b128 v[98:101], v245
	ds_read_b128 v[102:105], v245 offset:8192
	ds_read_b128 v[106:109], v246
	ds_read_b128 v[110:113], v246 offset:8192
	ds_read_b128 v[114:117], v247
	ds_read_b128 v[118:121], v247 offset:8192
	ds_read_b128 v[122:125], v250
	ds_read_b128 v[126:129], v250 offset:8192
	ds_read_b128 v[130:133], v184 offset:16384
	ds_read_b128 v[134:137], v184 offset:20480
	ds_read_b128 v[138:141], v184 offset:24576
	ds_read_b128 v[142:145], v184 offset:28672
	s_waitcnt lgkmcnt(12)
	v_max_f32_e32 v68, v68, v68
	v_max_f32_e32 v66, v66, v66
	v_max_f32_e32 v66, v66, v68
	v_max_f32_e32 v68, v72, v72
	v_max_f32_e32 v70, v70, v70
	v_max_f32_e32 v68, v70, v68
	v_max_f32_e32 v70, v80, v80
	v_max_f32_e32 v72, v78, v78
	v_max_f32_e32 v70, v72, v70
	v_max3_f32 v70, v74, v76, v70
	v_max3_f32 v66, v66, v68, v70
	v_max_f32_e32 v68, v69, v69
	v_max_f32_e32 v67, v67, v67
	v_min_f32_e32 v67, v67, v68
	v_max_f32_e32 v68, v73, v73
	v_max_f32_e32 v69, v71, v71
	v_min_f32_e32 v68, v69, v68
	v_max_f32_e32 v69, v81, v81
	v_max_f32_e32 v70, v79, v79
	v_min_f32_e32 v69, v70, v69
	v_min3_f32 v69, v75, v77, v69
	v_min3_f32 v67, v67, v68, v69
	v_readfirstlane_b32 s96, v66
	v_readfirstlane_b32 s38, v67
	s_cmp_lt_i32 s45, 1
	s_mov_b64 s[20:21], -1
	s_cbranch_scc1 .LBB0_370

; #define LAS __attribute__((address_space(3)))
; template <int TYPE> ...
;     ...
;     for (int dc = 0; dc < 4; ++dc) {
;         const bf16x8 a0 = *(const LAS bf16x8*)(lds + kad[dc]);
;         const bf16x8 a1 = *(const LAS bf16x8*)(lds + kad[dc] + 8192);
;     ...
;             const bf16x8 vf = *(const LAS bf16x8*)(lds + vad[c] + d * 4096);
.LBB0_369:
	ds_read_b128 v[98:101], v245
	ds_read_b128 v[102:105], v245 offset:8192
	ds_read_b128 v[106:109], v246
	ds_read_b128 v[110:113], v246 offset:8192
	ds_read_b128 v[114:117], v247
	ds_read_b128 v[118:121], v247 offset:8192
	ds_read_b128 v[122:125], v250
	ds_read_b128 v[126:129], v250 offset:8192
	ds_read_b128 v[130:133], v184 offset:16384
	ds_read_b128 v[134:137], v184 offset:20480
	ds_read_b128 v[138:141], v184 offset:24576
	ds_read_b128 v[142:145], v184 offset:28672
	s_cmp_lt_i32 s45, 1
	s_mov_b64 s[20:21], -1
	s_cbranch_scc0 .LBB0_368

; __device__ __forceinline__ float nopack(float v) { asm("" : "+v"(v)); return v; }
; #define A_GEN(dst) do { int tn_; \
;         if (dir > 0) { tn_ = tlast + 1; if (tn_ >= NT2 || (float)(tn_ * 128) > blkR) { dir = -1; tn_ = tstart2 - 1; if (tn_ < 0 || (float)(tn_ * 128 + 127) < blkL) tn_ = -1; } } \
;         else { tn_ = tlast - 1; if (tn_ < 0 || (float)(tn_ * 128 + 127) < blkL) tn_ = -1; } \
;         if (tn_ >= 0) tlast = tn_; dst = tn_; } while (0)
; template <int TYPE> ...
;     ...
;         const float sg = nslope, bl = __builtin_fmaf(sg, dbase, -mref);
; #pragma unroll
;         for (int r = 0; r < 16; ++r) { const float c = (float)((r & 7) + 16 * (r >> 3)); s0[r] = nopack(__builtin_fmaf(sg, c, bl)); s1[r] = nopack(__builtin_fmaf(sg, c + 32.f, bl)); }
; __device__ __forceinline__ void unitA(LAS char* lds, const gbf* PROJ, const gbf* VT, gbf* Y, const int S, const int tok0, const int h, const int qblk,
;                                       const float lam, const float oml, const gfl* subln, const float kn2a, const float kn2b, const int tid_) {
;     ...
;         A_GEN(tB); if (tB >= 0) { A_ISSUE(2 * tB, 2 * ((it + 1) & 1)); A_ISSUE(2 * tB + 1, 2 * ((it + 1) & 1) + 1); }
; #pragma unroll
;         for (int sub = 0; sub < 2; ++sub) {
;           const int kv0 = tA * 128 + sub * 64, sb = (2 * (it & 1) + sub) * A_STAGE; const float dbase = (float)kv0 - qposf;
;           int kad[4], vad[4];
; #pragma unroll
;           for (int k = 0; k < 4; ++k) { kad[k] = kbase[k] + sb; vad[k] = vbase[k] + sb; }
;           const int dmin = kv0 > q0 ? kv0 - (q0 + 31) : q0 - (kv0 + 63);
;           const bool frst = it == 0 && sub == 0;
;           const bool chk = frst || !(ew - slope2 * (float)dmin < 7.5f);
;           if (kv0 + 63 < q0 || kv0 > q0 + 31) wave_tileA<0>(lds, kad, vad, qf, o, mref, lsum, dbase, kv0 > q0 ? nslope : -nslope, wsf, r32, hi, frst, chk);
.LBB0_381:
	s_andn2_b64 vcc, exec, s[22:23]
	s_cbranch_vccnz .LBB0_383
	s_and_b32 s89, s44, 0x10000
	s_lshl_b32 s52, s97, 7
	s_mul_i32 s54, s52, 0x1e00
	s_add_u32 s54, s48, s54
	s_addc_u32 s55, s49, 0
	s_add_u32 s56, s54, 0x78000
	s_addc_u32 s57, s55, 0
	s_lshl_b32 s52, s52, 1
	s_add_u32 s58, s50, s52
	s_addc_u32 s59, s51, 0
	s_add_u32 s60, s58, 0x80
	s_addc_u32 s61, s59, 0
	s_xor_b32 s52, s89, 0x10000
	s_add_i32 s62, s91, s52
.LBB0_383:
	s_lshl_b32 s76, s24, 7
	s_cmp_eq_u32 s36, 0
	s_cselect_b64 s[22:23], -1, 0
	s_or_b32 s43, s76, 63
	s_cmp_gt_i32 s88, s43
	s_cselect_b64 s[26:27], -1, 0
	s_cmp_gt_i32 s76, s2
	s_cselect_b64 s[28:29], -1, 0
	v_cvt_f32_u32_e32 v208, s76
	s_or_b64 s[24:25], s[26:27], s[28:29]
	v_sub_f32_e32 v208, v208, v236
	s_andn2_b64 vcc, exec, s[24:25]
	s_cbranch_vccnz .Lattq_t2_s0
	v_cndmask_b32_e64 v201, v211, -v211, s[28:29]
	s_sub_i32 s26, s76, s2
	s_sub_i32 s27, s88, s43
	s_and_b64 s[28:29], s[28:29], exec
	s_cselect_b32 s26, s26, s27
	v_fma_f32 v251, v201, v208, -v204
	v_cvt_f32_i32_e32 v249, s26
	v_fma_f32 v249, -v211, v249, v244
	v_mov_b32_e32 v66, v251
	v_fmamk_f32 v82, v201, 0x42000000, v251
	v_add_f32_e32 v67, v201, v251
	v_fmamk_f32 v83, v201, 0x42040000, v251
	v_fma_f32 v68, 2.0, v201, v251
	v_fmamk_f32 v84, v201, 0x42080000, v251
	v_fmamk_f32 v69, v201, 0x40400000, v251
	v_fmamk_f32 v85, v201, 0x420c0000, v251
	v_fma_f32 v70, 4.0, v201, v251
	v_fmamk_f32 v86, v201, 0x42100000, v251
	v_fmamk_f32 v71, v201, 0x40a00000, v251
	v_fmamk_f32 v87, v201, 0x42140000, v251
	v_fmamk_f32 v72, v201, 0x40c00000, v251
	v_fmamk_f32 v88, v201, 0x42180000, v251
	v_fmamk_f32 v73, v201, 0x40e00000, v251
	v_fmamk_f32 v89, v201, 0x421c0000, v251
	v_fmamk_f32 v74, v201, 0x41800000, v251
	v_fmamk_f32 v90, v201, 0x42400000, v251
	v_fmamk_f32 v75, v201, 0x41880000, v251
	v_fmamk_f32 v91, v201, 0x42440000, v251
	v_fmamk_f32 v76, v201, 0x41900000, v251
	v_fmamk_f32 v92, v201, 0x42480000, v251
	v_fmamk_f32 v77, v201, 0x41980000, v251
	v_fmamk_f32 v93, v201, 0x424c0000, v251
	v_fmamk_f32 v78, v201, 0x41a00000, v251
	v_fmamk_f32 v94, v201, 0x42500000, v251
	v_fmamk_f32 v79, v201, 0x41a80000, v251
	v_fmamk_f32 v95, v201, 0x42540000, v251
	v_fmamk_f32 v80, v201, 0x41b00000, v251
	v_fmamk_f32 v96, v201, 0x42580000, v251
	v_fmamk_f32 v81, v201, 0x41b80000, v251
	v_fmamk_f32 v97, v201, 0x425c0000, v251
	v_cmp_ngt_f32_e32 vcc, s14, v249
	s_or_b64 s[24:25], s[22:23], vcc
	s_branch .Lattq_qk_s0

; #define LAS __attribute__((address_space(3)))
; __device__ __forceinline__ float max_x32(float v) { auto rr = __builtin_amdgcn_permlane32_swap(__float_as_uint(v), __float_as_uint(v), false, false); return __builtin_fmaxf(__uint_as_float(rr[0]), __uint_as_float(rr[1])); }
; __device__ __forceinline__ float max3f(float a, float b, float c) { float r; asm("v_max3_f32 %0, %1, %2, %3" : "=v"(r) : "v"(a), "v"(b), "v"(c)); return r; }
; __device__ __forceinline__ float max2f(float a, float b) { float r; asm("v_max_f32_e32 %0, %1, %2" : "=v"(r) : "v"(a), "v"(b)); return r; }
; __device__ __forceinline__ int crow(int r, int hi) { return (r & 3) + 8 * (r >> 2) + 4 * hi; }
; template <int TYPE> ...
;     ...
; #pragma unroll
;     for (int dc = 0; dc < 4; ++dc) {
;         const bf16x8 a0 = *(const LAS bf16x8*)(lds + kad[dc]);
;         const bf16x8 a1 = *(const LAS bf16x8*)(lds + kad[dc] + 8192);
;         s0 = __builtin_amdgcn_mfma_f32_32x32x16_bf16(a0, qf[dc], s0, 0, 0, 0);
;         s1 = __builtin_amdgcn_mfma_f32_32x32x16_bf16(a1, qf[dc], s1, 0, 0, 0);
;     }
;     if (chk) {
;     asm volatile("s_nop 15\n\ts_nop 7" : "+v"(s0), "+v"(s1));
;     float mx = max3f(s0[0], s1[0], s0[1]), mx2 = max3f(s1[1], s0[2], s1[2]);
; #pragma unroll
;     for (int r = 3; r < 15; r += 2) { mx = max3f(mx, s0[r], s1[r]); mx2 = max3f(mx2, s0[r + 1], s1[r + 1]); }
;     mx = max3f(mx, s0[15], s1[15]); mx = max2f(mx, mx2);
;     mx = max_x32(mx);
;     if (first || __any(mx > 8.f)) {
;         const float dl = first ? mx : __builtin_fmaxf(mx, 0.f), alpha = __builtin_amdgcn_exp2f(-dl);
;         lsum *= alpha; mref += dl;
; #pragma unroll
;         for (int r = 0; r < 16; ++r) { s0[r] -= dl; s1[r] -= dl; }
;         if (hi == 0) wsf[r32] = alpha;
; #pragma unroll
;         for (int r = 0; r < 16; ++r) { const float al = wsf[crow(r, hi)];
; #pragma unroll
;             for (int d = 0; d < 4; ++d) o[d][r] *= al; }
;     }
.Lattq_qk_s0:
	s_waitcnt lgkmcnt(4)
	s_nop 1
	s_cmp_gt_i32 s97, -1
	s_cbranch_scc0 .Lattq_qknd_s0
	s_mov_b32 m0, s62
	v_mfma_f32_32x32x16_bf16 v[66:81], v[98:101], v[162:165], v[66:81]
	global_load_lds_dwordx4 v180, s[54:55]
	s_add_i32 m0, s62, 0x400
	v_mfma_f32_32x32x16_bf16 v[82:97], v[102:105], v[162:165], v[82:97]
	global_load_lds_dwordx4 v196, s[54:55]
	ds_read_b128 v[146:149], v185 offset:16384
	ds_read_b128 v[150:153], v185 offset:20480
	s_add_i32 m0, s62, 0x4000
	v_mfma_f32_32x32x16_bf16 v[66:81], v[106:109], v[166:169], v[66:81]
	global_load_lds_dwordx4 v182, s[58:59]
	s_add_i32 m0, s62, 0x4400
	v_mfma_f32_32x32x16_bf16 v[82:97], v[110:113], v[166:169], v[82:97]
	global_load_lds_dwordx4 v198, s[58:59]
	ds_read_b128 v[154:157], v185 offset:24576
	ds_read_b128 v[158:161], v185 offset:28672
	s_add_i32 m0, s62, 0x8000
	v_mfma_f32_32x32x16_bf16 v[66:81], v[114:117], v[170:173], v[66:81]
	global_load_lds_dwordx4 v180, s[56:57]
	s_add_i32 m0, s62, 0x8400
	v_mfma_f32_32x32x16_bf16 v[82:97], v[118:121], v[170:173], v[82:97]
	global_load_lds_dwordx4 v196, s[56:57]
	ds_read_b128 v[98:101], v186 offset:16384
	ds_read_b128 v[102:105], v186 offset:20480
	ds_read_b128 v[106:109], v186 offset:24576
	ds_read_b128 v[110:113], v186 offset:28672
	s_add_i32 m0, s62, 0xc000
	v_mfma_f32_32x32x16_bf16 v[66:81], v[122:125], v[174:177], v[66:81]
	global_load_lds_dwordx4 v182, s[60:61]
	s_add_i32 m0, s62, 0xc400
	v_mfma_f32_32x32x16_bf16 v[82:97], v[126:129], v[174:177], v[82:97]
	global_load_lds_dwordx4 v198, s[60:61]
	s_branch .Lattq_qkdone_s0
.Lattq_qknd_s0:
	v_mfma_f32_32x32x16_bf16 v[66:81], v[98:101], v[162:165], v[66:81]
	v_mfma_f32_32x32x16_bf16 v[82:97], v[102:105], v[162:165], v[82:97]
	ds_read_b128 v[146:149], v185 offset:16384
	ds_read_b128 v[150:153], v185 offset:20480
	v_mfma_f32_32x32x16_bf16 v[66:81], v[106:109], v[166:169], v[66:81]
	v_mfma_f32_32x32x16_bf16 v[82:97], v[110:113], v[166:169], v[82:97]
	ds_read_b128 v[154:157], v185 offset:24576
	ds_read_b128 v[158:161], v185 offset:28672
	v_mfma_f32_32x32x16_bf16 v[66:81], v[114:117], v[170:173], v[66:81]
	v_mfma_f32_32x32x16_bf16 v[82:97], v[118:121], v[170:173], v[82:97]
	ds_read_b128 v[98:101], v186 offset:16384
	ds_read_b128 v[102:105], v186 offset:20480
	ds_read_b128 v[106:109], v186 offset:24576
	ds_read_b128 v[110:113], v186 offset:28672
	v_mfma_f32_32x32x16_bf16 v[66:81], v[122:125], v[174:177], v[66:81]
	v_mfma_f32_32x32x16_bf16 v[82:97], v[126:129], v[174:177], v[82:97]
.Lattq_qkdone_s0:
	s_waitcnt lgkmcnt(11)
	ds_read_b128 v[114:117], v187 offset:16384
	ds_read_b128 v[118:121], v187 offset:20480
	ds_read_b128 v[122:125], v187 offset:24576
	ds_read_b128 v[126:129], v187 offset:28672
	s_nop 6
	s_andn2_b64 vcc, exec, s[24:25]
	s_cbranch_vccnz .Lattq_exp_s0
	v_max3_f32 v201, v66, v67, v68
	v_max3_f32 v251, v82, v83, v84
	v_max3_f32 v201, v201, v69, v70
	v_max3_f32 v251, v251, v85, v86
	v_max3_f32 v201, v201, v71, v72
	v_max3_f32 v251, v251, v87, v88
	v_max3_f32 v201, v201, v73, v74
	v_max3_f32 v251, v251, v89, v90
	v_max3_f32 v201, v201, v75, v76
	v_max3_f32 v251, v251, v91, v92
	v_max3_f32 v201, v201, v77, v78
	v_max3_f32 v251, v251, v93, v94
	v_max3_f32 v201, v201, v79, v80
	v_max3_f32 v251, v251, v95, v96
	v_max3_f32 v201, v201, v81, v97
	v_max_f32_e32 v201, v201, v251
	v_mov_b32_e32 v251, v201
	s_nop 1
	v_permlane32_swap_b32_e32 v201, v251
	v_max_f32_e32 v201, v201, v251
	v_cmp_lt_f32_e32 vcc, s18, v201
	s_or_b64 s[24:25], s[22:23], vcc
	s_cmp_lg_u64 s[24:25], 0
	s_cbranch_scc0 .Lattq_exp_s0
	v_max_f32_e32 v251, 0, v201
	v_cndmask_b32_e64 v201, v251, v201, s[22:23]
	s_nop 0
	v_exp_f32_e64 v251, -v201
	s_and_saveexec_b64 s[24:25], s[12:13]
	ds_write_b32 v214, v251
	s_or_b64 exec, exec, s[24:25]
	v_mul_f32_e32 v248, v248, v251
	v_add_f32_e32 v204, v204, v201
	v_sub_f32_e32 v66, v66, v201
	v_sub_f32_e32 v82, v82, v201
	v_sub_f32_e32 v67, v67, v201
	v_sub_f32_e32 v83, v83, v201
	v_sub_f32_e32 v68, v68, v201
	v_sub_f32_e32 v84, v84, v201
	v_sub_f32_e32 v69, v69, v201
	v_sub_f32_e32 v85, v85, v201
	v_sub_f32_e32 v70, v70, v201
	v_sub_f32_e32 v86, v86, v201
	v_sub_f32_e32 v71, v71, v201
	v_sub_f32_e32 v87, v87, v201
	v_sub_f32_e32 v72, v72, v201
	v_sub_f32_e32 v88, v88, v201
	v_sub_f32_e32 v73, v73, v201
	v_sub_f32_e32 v89, v89, v201
	v_sub_f32_e32 v74, v74, v201
	v_sub_f32_e32 v90, v90, v201
	v_sub_f32_e32 v75, v75, v201
	v_sub_f32_e32 v91, v91, v201
	v_sub_f32_e32 v76, v76, v201
	v_sub_f32_e32 v92, v92, v201
	v_sub_f32_e32 v77, v77, v201
	v_sub_f32_e32 v93, v93, v201
	v_sub_f32_e32 v78, v78, v201
	v_sub_f32_e32 v94, v94, v201
	v_sub_f32_e32 v79, v79, v201
	v_sub_f32_e32 v95, v95, v201
	v_sub_f32_e32 v80, v80, v201
	v_sub_f32_e32 v96, v96, v201
	v_sub_f32_e32 v81, v81, v201
	v_sub_f32_e32 v97, v97, v201
	v_add_u32_e32 v249, s42, v0
	ds_read_b128 v[192:195], v249
	s_waitcnt lgkmcnt(0)
	v_pk_mul_f32 v[2:3], v[2:3], v[192:193]
	v_pk_mul_f32 v[4:5], v[4:5], v[194:195]
	v_pk_mul_f32 v[18:19], v[18:19], v[192:193]
	v_pk_mul_f32 v[20:21], v[20:21], v[194:195]
	v_pk_mul_f32 v[34:35], v[34:35], v[192:193]
	v_pk_mul_f32 v[36:37], v[36:37], v[194:195]
	v_pk_mul_f32 v[50:51], v[50:51], v[192:193]
	v_pk_mul_f32 v[52:53], v[52:53], v[194:195]
	ds_read_b128 v[192:195], v249 offset:32
	s_waitcnt lgkmcnt(0)
	v_pk_mul_f32 v[6:7], v[6:7], v[192:193]
	v_pk_mul_f32 v[8:9], v[8:9], v[194:195]
	v_pk_mul_f32 v[22:23], v[22:23], v[192:193]
	v_pk_mul_f32 v[24:25], v[24:25], v[194:195]
	v_pk_mul_f32 v[38:39], v[38:39], v[192:193]
	v_pk_mul_f32 v[40:41], v[40:41], v[194:195]
	v_pk_mul_f32 v[54:55], v[54:55], v[192:193]
	v_pk_mul_f32 v[56:57], v[56:57], v[194:195]
	ds_read_b128 v[192:195], v249 offset:64
	s_waitcnt lgkmcnt(0)
	v_pk_mul_f32 v[10:11], v[10:11], v[192:193]
	v_pk_mul_f32 v[12:13], v[12:13], v[194:195]
	v_pk_mul_f32 v[26:27], v[26:27], v[192:193]
	v_pk_mul_f32 v[28:29], v[28:29], v[194:195]
	v_pk_mul_f32 v[42:43], v[42:43], v[192:193]
	v_pk_mul_f32 v[44:45], v[44:45], v[194:195]
	v_pk_mul_f32 v[58:59], v[58:59], v[192:193]
	v_pk_mul_f32 v[60:61], v[60:61], v[194:195]
	ds_read_b128 v[192:195], v249 offset:96
	s_waitcnt lgkmcnt(0)
	v_pk_mul_f32 v[14:15], v[14:15], v[192:193]
	v_pk_mul_f32 v[16:17], v[16:17], v[194:195]
	v_pk_mul_f32 v[30:31], v[30:31], v[192:193]
	v_pk_mul_f32 v[32:33], v[32:33], v[194:195]
	v_pk_mul_f32 v[46:47], v[46:47], v[192:193]
	v_pk_mul_f32 v[48:49], v[48:49], v[194:195]
	v_pk_mul_f32 v[62:63], v[62:63], v[192:193]
	v_pk_mul_f32 v[64:65], v[64:65], v[194:195]
